# v117 + static s_setprio 1 for waves 4-7 in LayerNorm/post phases
# baseline (speedup 1.0000x reference)
.LBB0_758:
	s_mov_b64 s[4:5], s[0:1]
	s_load_dword s3, s[4:5], 0xe8
	s_waitcnt lgkmcnt(0)
	s_cmp_gt_i32 s3, 6
	s_cbranch_scc1 .LBB0_764
	s_mov_b64 s[4:5], s[0:1]
	s_load_dword s3, s[4:5], 0xec
	s_waitcnt lgkmcnt(0)
	s_cmp_lt_i32 s3, 7
	s_cbranch_scc1 .LBB0_764
	v_cmp_lt_u32_e32 vcc, 0xff, v190
	s_cbranch_vccz .Llnprio_4
	s_setprio 1
.Llnprio_4:
	s_cmp_eq_u32 s24, 0x100
	s_cbranch_scc0 .Lpost_orig
	s_load_dwordx2 s[16:17], s[0:1], 0xe0
	s_load_dwordx2 s[4:5], s[0:1], 0xd8
	s_load_dwordx2 s[18:19], s[0:1], 0x70
	s_load_dwordx2 s[20:21], s[0:1], 0x78
	v_lshlrev_b32_e32 v1, 3, v190
	v_lshrrev_b32_e32 v2, 4, v190
	v_lshlrev_b32_e32 v2, 2, v2
	v_lshlrev_b32_e32 v5, 4, v190
	v_mov_b32_e32 v3, 0x260
	v_mov_b32_e32 v4, 0x3a27c5ac
	s_mov_b32 s3, 0xf800000
	s_lshl_b32 s22, s2, 18
	s_lshl_b32 s23, s2, 13
	s_waitcnt lgkmcnt(0)
	global_load_dwordx4 v[8:11], v5, s[18:19]
	global_load_dwordx4 v[12:15], v5, s[20:21]
	s_add_u32 s4, s4, s22
	s_addc_u32 s5, s5, 0
	s_add_u32 s8, s16, 0x1c100000
	s_addc_u32 s9, s17, 0
	s_add_u32 s8, s8, s22
	s_addc_u32 s9, s9, 0
	s_add_u32 s10, s16, 0x20100000
	s_addc_u32 s11, s17, 0
	s_add_u32 s10, s10, s22
	s_addc_u32 s11, s11, 0
	s_add_u32 s12, s16, 0x24100000
	s_addc_u32 s13, s17, 0
	s_add_u32 s12, s12, s23
	s_addc_u32 s13, s13, 0
	s_add_u32 s14, s16, 0x24300000
	s_addc_u32 s15, s17, 0
	s_add_u32 s14, s14, s22
	s_addc_u32 s15, s15, 0
	global_load_dwordx2 v[16:17], v1, s[4:5] nt
	global_load_dwordx2 v[18:19], v1, s[8:9] nt
	global_load_dwordx2 v[20:21], v1, s[10:11] nt
	global_load_dword v22, v2, s[12:13] nt
	s_add_u32 s4, s4, 0x1000
	s_addc_u32 s5, s5, 0
	s_add_u32 s8, s8, 0x1000
	s_addc_u32 s9, s9, 0
	s_add_u32 s10, s10, 0x1000
	s_addc_u32 s11, s11, 0
	s_add_u32 s12, s12, 0x80
	s_addc_u32 s13, s13, 0
	global_load_dwordx2 v[24:25], v1, s[4:5] nt
	global_load_dwordx2 v[26:27], v1, s[8:9] nt
	global_load_dwordx2 v[28:29], v1, s[10:11] nt
	global_load_dword v30, v2, s[12:13] nt
	s_add_u32 s4, s4, 0x1000
	s_addc_u32 s5, s5, 0
	s_add_u32 s8, s8, 0x1000
	s_addc_u32 s9, s9, 0
	s_add_u32 s10, s10, 0x1000
	s_addc_u32 s11, s11, 0
	s_add_u32 s12, s12, 0x80
	s_addc_u32 s13, s13, 0
	global_load_dwordx2 v[32:33], v1, s[4:5] nt
	global_load_dwordx2 v[34:35], v1, s[8:9] nt
	global_load_dwordx2 v[36:37], v1, s[10:11] nt
	global_load_dword v38, v2, s[12:13] nt
	s_add_u32 s4, s4, 0x1000
	s_addc_u32 s5, s5, 0
	s_add_u32 s8, s8, 0x1000
	s_addc_u32 s9, s9, 0
	s_add_u32 s10, s10, 0x1000
	s_addc_u32 s11, s11, 0
	s_add_u32 s12, s12, 0x80
	s_addc_u32 s13, s13, 0
	global_load_dwordx2 v[40:41], v1, s[4:5] nt
	global_load_dwordx2 v[42:43], v1, s[8:9] nt
	global_load_dwordx2 v[44:45], v1, s[10:11] nt
	global_load_dword v46, v2, s[12:13] nt
	s_add_u32 s4, s4, 0x1000
	s_addc_u32 s5, s5, 0
	s_add_u32 s8, s8, 0x1000
	s_addc_u32 s9, s9, 0
	s_add_u32 s10, s10, 0x1000
	s_addc_u32 s11, s11, 0
	s_add_u32 s12, s12, 0x80
	s_addc_u32 s13, s13, 0
	global_load_dword v80, v2, s[12:13]
	global_load_dword v81, v2, s[12:13]
	global_load_dword v82, v2, s[12:13]
	global_load_dword v83, v2, s[12:13]
	s_mov_b32 s26, 8

.LBB0_924:
	s_mov_b64 s[4:5], s[0:1]
	s_load_dword s3, s[4:5], 0xe8
	s_waitcnt lgkmcnt(0)
	s_cmp_gt_i32 s3, 8
	s_cbranch_scc1 .LBB0_933
	s_mov_b64 s[4:5], s[0:1]
	s_load_dword s3, s[4:5], 0xec
	s_waitcnt lgkmcnt(0)
	s_cmp_lt_i32 s3, 9
	s_cbranch_scc1 .LBB0_933
	s_mov_b64 s[10:11], s[0:1]
	s_mov_b64 s[6:7], s[0:1]
	s_mov_b64 s[12:13], s[0:1]
	s_mov_b64 s[16:17], s[0:1]
	s_mov_b64 s[4:5], s[0:1]
	v_mov_b32_e32 v1, v190
	s_mov_b32 s8, s2
	s_lshl_b32 s8, s8, 3
	v_readfirstlane_b32 s3, v1
	s_ashr_i32 s3, s3, 6
	s_add_i32 s8, s8, s3
	s_cmpk_gt_i32 s8, 0x3fff
	s_cbranch_scc1 .LBB0_933
	v_cmp_lt_u32_e32 vcc, 0xff, v190
	s_cbranch_vccz .Llnprio_0
	s_setprio 1
.Llnprio_0:
	s_load_dwordx2 s[22:23], s[10:11], 0xe0
	s_ashr_i32 s9, s8, 31
	s_lshl_b32 s10, s24, 3
	s_lshl_b64 s[18:19], s[8:9], 12
	s_waitcnt vmcnt(0)
	v_and_b32_e32 v6, 63, v1
	s_waitcnt lgkmcnt(0)
	s_add_u32 s14, s22, s18
	s_addc_u32 s15, s23, s19
	v_lshlrev_b32_e32 v34, 4, v6
	v_mov_b32_e32 v35, 0
	v_lshl_add_u64 v[2:3], s[14:15], 0, v[34:35]
	s_mov_b64 s[14:15], 0x20100000
	s_mov_b32 s3, 0x20100000
	v_lshl_add_u64 v[4:5], v[2:3], 0, s[14:15]
	v_add_co_u32_e32 v2, vcc, s3, v2
	global_load_dwordx4 v[26:29], v[4:5], off offset:1024
	global_load_dwordx4 v[22:25], v[4:5], off offset:2048
	global_load_dwordx4 v[18:21], v[4:5], off offset:3072
	v_addc_co_u32_e32 v3, vcc, 0, v3, vcc
	global_load_dwordx4 v[30:33], v[2:3], off
	s_load_dwordx2 s[28:29], s[6:7], 0xb8
	s_load_dwordx2 s[30:31], s[12:13], 0xc0
	s_load_dwordx2 s[20:21], s[16:17], 0xe0
	s_load_dwordx2 s[14:15], s[4:5], 0xe0
	v_mbcnt_lo_u32_b32 v2, -1, 0
	v_mbcnt_hi_u32_b32 v10, -1, v2
	v_and_b32_e32 v12, 64, v10
	v_xor_b32_e32 v11, 16, v10
	v_add_u32_e32 v12, 64, v12
	v_xor_b32_e32 v13, 32, v10
	v_cmp_lt_i32_e64 s[6:7], v11, v12
	s_waitcnt lgkmcnt(0)
	s_cmp_lg_u64 s[14:15], 0
	v_cmp_eq_u32_e32 vcc, 0, v6
	v_cndmask_b32_e64 v11, v10, v11, s[6:7]
	v_cmp_lt_i32_e64 s[6:7], v13, v12
	s_cselect_b64 s[4:5], -1, 0
	s_and_b64 s[12:13], s[4:5], vcc
	v_cndmask_b32_e64 v10, v10, v13, s[6:7]
	s_lshl_b64 s[6:7], s[8:9], 3
	s_add_u32 s14, s14, s6
	s_addc_u32 s15, s15, s7
	s_ashr_i32 s11, s10, 31
	s_lshl_b64 s[16:17], s[10:11], 3
	s_add_u32 s18, s20, s18
	s_addc_u32 s19, s21, s19
	s_add_i32 s4, s8, s10
	v_lshlrev_b32_e32 v2, 5, v6
	s_ashr_i32 s5, s4, 31
	v_mov_b32_e32 v3, v35
	v_mov_b32_e32 v5, v35
	v_mov_b32_e32 v7, v35
	v_mov_b32_e32 v9, v35
	v_or_b32_e32 v4, 0x800, v2
	v_or_b32_e32 v6, 0x1000, v2
	v_or_b32_e32 v8, 0x1800, v2
	s_lshl_b64 s[20:21], s[10:11], 12
	s_lshl_b64 s[4:5], s[4:5], 12
	v_lshlrev_b32_e32 v70, 2, v11
	v_lshlrev_b32_e32 v71, 2, v10
	v_lshl_add_u64 v[36:37], s[28:29], 0, v[2:3]
	v_lshl_add_u64 v[38:39], s[30:31], 0, v[2:3]
	v_lshl_add_u64 v[40:41], s[28:29], 0, v[4:5]
	v_lshl_add_u64 v[42:43], s[30:31], 0, v[4:5]
	v_lshl_add_u64 v[44:45], s[28:29], 0, v[6:7]
	v_lshl_add_u64 v[46:47], s[30:31], 0, v[6:7]
	v_lshl_add_u64 v[48:49], s[28:29], 0, v[8:9]
	v_lshl_add_u64 v[50:51], s[30:31], 0, v[8:9]
	global_load_dwordx4 v[100:103], v[36:37], off
	global_load_dwordx4 v[104:107], v[36:37], off offset:16
	global_load_dwordx4 v[108:111], v[38:39], off
	global_load_dwordx4 v[112:115], v[38:39], off offset:16
	global_load_dwordx4 v[116:119], v[40:41], off
	global_load_dwordx4 v[120:123], v[40:41], off offset:16
	global_load_dwordx4 v[124:127], v[42:43], off
	global_load_dwordx4 v[128:131], v[42:43], off offset:16
	global_load_dwordx4 v[132:135], v[44:45], off
	global_load_dwordx4 v[136:139], v[44:45], off offset:16
	global_load_dwordx4 v[140:143], v[46:47], off
	global_load_dwordx4 v[144:147], v[46:47], off offset:16
	global_load_dwordx4 v[148:151], v[48:49], off
	global_load_dwordx4 v[152:155], v[48:49], off offset:16
	global_load_dwordx4 v[156:159], v[50:51], off
	global_load_dwordx4 v[160:163], v[50:51], off offset:16
	s_add_u32 s22, s22, s4
	v_mov_b32_e32 v1, 0x3727c5ac
	s_mov_b32 s3, 0xf800000
	v_mov_b32_e32 v69, 0x260
	s_mov_b32 s26, 0x8100000
	s_addc_u32 s23, s23, s5
	s_waitcnt vmcnt(0)
	v_mov_b64_e32 v[10:11], v[26:27]
	s_waitcnt vmcnt(2)
	v_mov_b64_e32 v[6:7], v[22:23]
	s_waitcnt vmcnt(1)
	v_mov_b64_e32 v[2:3], v[18:19]
	v_mov_b64_e32 v[4:5], v[20:21]
	v_mov_b64_e32 v[8:9], v[24:25]
	s_waitcnt vmcnt(0)
	v_mov_b64_e32 v[14:15], v[30:31]
	v_mov_b64_e32 v[12:13], v[28:29]
	v_mov_b64_e32 v[16:17], v[32:33]
	s_branch .LBB0_929

.LBB0_1331:
	s_mov_b64 s[4:5], s[0:1]
	s_load_dword s4, s[4:5], 0xe8
	s_waitcnt lgkmcnt(0)
	s_cmp_gt_i32 s4, 21
	s_cbranch_scc1 .LBB0_1340
	s_mov_b64 s[4:5], s[0:1]
	s_load_dword s4, s[4:5], 0xec
	s_waitcnt lgkmcnt(0)
	s_cmp_lt_i32 s4, 22
	s_cbranch_scc1 .LBB0_1340
	s_mov_b64 s[4:5], s[0:1]
	s_mov_b64 s[6:7], s[0:1]
	s_mov_b64 s[14:15], s[0:1]
	s_mov_b64 s[8:9], s[0:1]
	s_mov_b64 s[12:13], s[0:1]
	v_mov_b32_e32 v0, v190
	s_nop 0
	v_readfirstlane_b32 s10, v0
	s_ashr_i32 s18, s10, 6
	s_mov_b32 s10, s2
	s_lshl_b32 s19, s10, 3
	s_add_i32 s10, s19, s18
	s_cmpk_gt_i32 s10, 0x3fff
	s_cbranch_scc1 .LBB0_1340
	v_cmp_lt_u32_e32 vcc, 0xff, v190
	s_cbranch_vccz .Llnprio_1
	s_setprio 1
.Llnprio_1:
	s_load_dwordx2 s[14:15], s[14:15], 0xc0
	s_nop 0
	s_load_dwordx2 s[22:23], s[6:7], 0xb8
	s_nop 0
	s_load_dwordx2 s[6:7], s[4:5], 0xe0
	s_waitcnt vmcnt(0)
	v_and_b32_e32 v6, 63, v0
	v_lshlrev_b32_e32 v0, 4, v6
	s_waitcnt lgkmcnt(0)
	s_add_u32 s4, s14, 0x2000
	s_addc_u32 s5, s15, 0
	s_add_u32 s14, s22, 0x2000
	s_addc_u32 s15, s23, 0
	s_ashr_i32 s11, s10, 31
	s_lshl_b64 s[22:23], s[10:11], 12
	s_add_u32 s26, s6, s22
	s_addc_u32 s27, s7, s23
	v_lshl_add_u64 v[2:3], s[26:27], 0, v[0:1]
	s_mov_b64 s[26:27], 0x20100000
	s_mov_b32 s21, 0x20100000
	v_lshl_add_u64 v[4:5], v[2:3], 0, s[26:27]
	v_add_co_u32_e32 v2, vcc, s21, v2
	global_load_dwordx4 v[26:29], v[4:5], off offset:1024
	global_load_dwordx4 v[22:25], v[4:5], off offset:2048
	global_load_dwordx4 v[18:21], v[4:5], off offset:3072
	v_addc_co_u32_e32 v3, vcc, 0, v3, vcc
	global_load_dwordx4 v[30:33], v[2:3], off
	s_load_dwordx2 s[26:27], s[8:9], 0xe0
	s_load_dwordx2 s[36:37], s[12:13], 0xe0
	v_and_b32_e32 v2, 64, v197
	v_xor_b32_e32 v4, 16, v197
	v_add_u32_e32 v10, 64, v2
	v_xor_b32_e32 v8, 32, v197
	v_cmp_lt_i32_e64 s[8:9], v4, v10
	v_lshlrev_b32_e32 v2, 5, v6
	v_mov_b32_e32 v3, v1
	v_cndmask_b32_e64 v11, v197, v4, s[8:9]
	v_cmp_lt_i32_e64 s[8:9], v8, v10
	v_mov_b32_e32 v5, v1
	v_mov_b32_e32 v7, v1
	v_mov_b32_e32 v9, v1
	v_cmp_eq_u32_e32 vcc, 0, v6
	v_cndmask_b32_e64 v10, v197, v8, s[8:9]
	v_or_b32_e32 v4, 0x800, v2
	v_or_b32_e32 v6, 0x1000, v2
	v_or_b32_e32 v8, 0x1800, v2
	s_waitcnt lgkmcnt(0)
	s_cmp_lg_u64 s[36:37], 0
	v_lshl_add_u64 v[34:35], s[4:5], 0, v[2:3]
	v_lshl_add_u64 v[36:37], s[4:5], 0, v[4:5]
	v_lshl_add_u64 v[38:39], s[4:5], 0, v[6:7]
	v_lshl_add_u64 v[40:41], s[4:5], 0, v[8:9]
	s_cselect_b64 s[4:5], -1, 0
	s_lshl_b64 s[8:9], s[10:11], 3
	s_and_b64 s[12:13], s[4:5], vcc
	v_lshl_add_u64 v[42:43], s[14:15], 0, v[2:3]
	v_lshl_add_u64 v[44:45], s[14:15], 0, v[4:5]
	v_lshl_add_u64 v[46:47], s[14:15], 0, v[6:7]
	v_lshl_add_u64 v[48:49], s[14:15], 0, v[8:9]
	global_load_dwordx4 v[86:89], v[34:35], off
	global_load_dwordx4 v[90:93], v[34:35], off offset:16
	global_load_dwordx4 v[94:97], v[42:43], off
	global_load_dwordx4 v[98:101], v[42:43], off offset:16
	global_load_dwordx4 v[102:105], v[36:37], off
	global_load_dwordx4 v[106:109], v[36:37], off offset:16
	global_load_dwordx4 v[110:113], v[44:45], off
	global_load_dwordx4 v[130:133], v[44:45], off offset:16
	global_load_dwordx4 v[134:137], v[38:39], off
	global_load_dwordx4 v[138:141], v[38:39], off offset:16
	global_load_dwordx4 v[142:145], v[46:47], off
	global_load_dwordx4 v[158:161], v[46:47], off offset:16
	global_load_dwordx4 v[162:165], v[40:41], off
	global_load_dwordx4 v[166:169], v[40:41], off offset:16
	global_load_dwordx4 v[170:173], v[48:49], off
	global_load_dwordx4 v[176:179], v[48:49], off offset:16
	s_add_u32 s14, s36, s8
	s_addc_u32 s15, s37, s9
	s_add_u32 s64, s26, s22
	s_addc_u32 s65, s27, s23
	s_add_i32 s4, s20, s18
	s_add_i32 s4, s4, s19
	s_ashr_i32 s5, s4, 31
	s_lshl_b64 s[4:5], s[4:5], 12
	v_lshlrev_b32_e32 v59, 2, v11
	v_lshlrev_b32_e32 v68, 2, v10
	s_add_u32 s68, s6, s4
	s_addc_u32 s69, s7, s5
	s_waitcnt vmcnt(0)
	v_mov_b64_e32 v[10:11], v[26:27]
	s_waitcnt vmcnt(2)
	v_mov_b64_e32 v[6:7], v[22:23]
	s_waitcnt vmcnt(1)
	v_mov_b64_e32 v[2:3], v[18:19]
	v_mov_b64_e32 v[4:5], v[20:21]
	v_mov_b64_e32 v[8:9], v[24:25]
	s_waitcnt vmcnt(0)
	v_mov_b64_e32 v[14:15], v[30:31]
	v_mov_b64_e32 v[12:13], v[28:29]
	v_mov_b64_e32 v[16:17], v[32:33]
	s_branch .LBB0_1336

.LBB0_1691:
	s_mov_b64 s[4:5], s[0:1]
	s_load_dword s4, s[4:5], 0xe8
	s_add_i32 s21, s21, 3
	s_waitcnt lgkmcnt(0)
	s_cmp_gt_i32 s4, s21
	s_cbranch_scc1 .LBB0_1715
	s_mov_b64 s[4:5], s[0:1]
	s_load_dword s4, s[4:5], 0xec
	s_waitcnt lgkmcnt(0)
	s_cmp_ge_i32 s21, s4
	s_mov_b32 s21, 0x12000
	s_cbranch_scc1 .LBB0_1715
	s_xor_b64 s[6:7], s[70:71], -1
	s_mov_b64 s[4:5], -1
	s_and_b64 vcc, exec, s[6:7]
	s_cbranch_vccz .LBB0_1702
	s_mov_b64 s[4:5], s[0:1]
	s_mov_b64 s[6:7], s[0:1]
	s_mov_b64 s[8:9], s[0:1]
	s_mov_b64 s[12:13], s[0:1]
	v_mov_b32_e32 v0, v190
	s_nop 0
	v_readfirstlane_b32 s10, v0
	s_ashr_i32 s18, s10, 6
	s_mov_b32 s10, s2
	s_lshl_b32 s19, s10, 3
	s_add_i32 s10, s19, s18
	s_cmpk_gt_i32 s10, 0x3fff
	s_cbranch_scc1 .LBB0_1701
	v_cmp_lt_u32_e32 vcc, 0xff, v190
	s_cbranch_vccz .Llnprio_2
	s_setprio 1
.Llnprio_2:
	s_load_dwordx2 s[8:9], s[8:9], 0xd0
	s_nop 0
	s_load_dwordx2 s[6:7], s[6:7], 0xc8
	s_nop 0
	s_load_dwordx2 s[4:5], s[4:5], 0xe0
	s_waitcnt vmcnt(0)
	v_and_b32_e32 v2, 63, v0
	v_lshlrev_b32_e32 v0, 4, v2
	s_waitcnt lgkmcnt(0)
	s_add_u32 s8, s8, 0x2000
	s_addc_u32 s9, s9, 0
	s_add_u32 s6, s6, 0x2000
	s_addc_u32 s7, s7, 0
	s_add_u32 s21, s4, 0x20100000
	s_addc_u32 s22, s5, 0
	s_ashr_i32 s11, s10, 31
	s_lshl_b64 s[4:5], s[10:11], 12
	s_add_u32 s4, s21, s4
	s_addc_u32 s5, s22, s5
	global_load_dwordx4 v[18:21], v0, s[4:5] offset:3072
	global_load_dwordx4 v[22:25], v0, s[4:5] offset:2048
	global_load_dwordx4 v[26:29], v0, s[4:5] offset:1024
	global_load_dwordx4 v[30:33], v0, s[4:5]
	s_load_dwordx2 s[14:15], s[12:13], 0xd8
	v_and_b32_e32 v6, 64, v197
	v_xor_b32_e32 v4, 16, v197
	v_add_u32_e32 v6, 64, v6
	v_xor_b32_e32 v8, 32, v197
	v_cmp_lt_i32_e32 vcc, v4, v6
	v_lshlrev_b32_e32 v2, 5, v2
	v_mov_b32_e32 v3, v1
	v_cndmask_b32_e32 v10, v197, v4, vcc
	v_cmp_lt_i32_e32 vcc, v8, v6
	v_mov_b32_e32 v5, v1
	v_mov_b32_e32 v7, v1
	v_mov_b32_e32 v9, v1
	v_cndmask_b32_e32 v11, v197, v8, vcc
	v_or_b32_e32 v4, 0x800, v2
	v_or_b32_e32 v6, 0x1000, v2
	v_or_b32_e32 v8, 0x1800, v2
	s_waitcnt lgkmcnt(0)
	s_cmp_lg_u64 s[14:15], 0
	v_lshl_add_u64 v[42:43], s[6:7], 0, v[2:3]
	v_lshl_add_u64 v[44:45], s[6:7], 0, v[4:5]
	v_lshl_add_u64 v[46:47], s[6:7], 0, v[6:7]
	v_lshl_add_u64 v[48:49], s[6:7], 0, v[8:9]
	s_cselect_b64 s[12:13], -1, 0
	s_add_i32 s6, s20, s18
	s_add_i32 s6, s6, s19
	s_ashr_i32 s7, s6, 31
	s_lshl_b64 s[6:7], s[6:7], 12
	s_add_u32 s6, s21, s6
	v_lshl_add_u64 v[34:35], s[8:9], 0, v[2:3]
	v_lshl_add_u64 v[36:37], s[8:9], 0, v[4:5]
	v_lshl_add_u64 v[38:39], s[8:9], 0, v[6:7]
	v_lshl_add_u64 v[40:41], s[8:9], 0, v[8:9]
	global_load_dwordx4 v[94:97], v[34:35], off
	global_load_dwordx4 v[98:101], v[34:35], off offset:16
	global_load_dwordx4 v[102:105], v[42:43], off
	global_load_dwordx4 v[106:109], v[42:43], off offset:16
	global_load_dwordx4 v[110:113], v[36:37], off
	global_load_dwordx4 v[130:133], v[36:37], off offset:16
	global_load_dwordx4 v[134:137], v[44:45], off
	global_load_dwordx4 v[138:141], v[44:45], off offset:16
	global_load_dwordx4 v[142:145], v[38:39], off
	global_load_dwordx4 v[158:161], v[38:39], off offset:16
	global_load_dwordx4 v[162:165], v[46:47], off
	global_load_dwordx4 v[166:169], v[46:47], off offset:16
	global_load_dwordx4 v[170:173], v[40:41], off
	global_load_dwordx4 v[176:179], v[40:41], off offset:16
	global_load_dwordx4 v[180:183], v[48:49], off
	global_load_dwordx4 v[184:187], v[48:49], off offset:16
	s_addc_u32 s7, s22, s7
	s_lshl_b64 s[8:9], s[10:11], 13
	v_lshl_add_u64 v[50:51], s[6:7], 0, v[0:1]
	s_add_u32 s6, s14, s8
	s_addc_u32 s7, s15, s9
	s_mov_b64 s[4:5], 0x1000
	v_lshl_add_u64 v[2:3], s[6:7], 0, v[2:3]
	v_lshlrev_b32_e32 v70, 2, v10
	v_lshlrev_b32_e32 v71, 2, v11
	v_lshl_add_u64 v[52:53], v[2:3], 0, s[4:5]
	s_mov_b32 s21, 0x12000
	s_waitcnt vmcnt(0)
	v_mov_b64_e32 v[2:3], v[18:19]
	s_waitcnt vmcnt(2)
	v_mov_b64_e32 v[6:7], v[22:23]
	s_waitcnt vmcnt(1)
	v_mov_b64_e32 v[10:11], v[26:27]
	s_waitcnt vmcnt(0)
	v_mov_b64_e32 v[14:15], v[30:31]
	v_mov_b64_e32 v[4:5], v[20:21]
	v_mov_b64_e32 v[8:9], v[24:25]
	v_mov_b64_e32 v[12:13], v[28:29]
	v_mov_b64_e32 v[16:17], v[32:33]
	s_branch .LBB0_1697

.LBB0_1702:
	s_andn2_b64 vcc, exec, s[4:5]
	s_cbranch_vccnz .LBB0_1715
	s_mov_b64 s[6:7], s[0:1]
	s_mov_b64 s[8:9], s[0:1]
	s_mov_b64 s[4:5], s[0:1]
	s_mov_b64 s[12:13], s[0:1]
	s_mov_b64 s[14:15], s[0:1]
	v_mov_b32_e32 v0, v190
	s_nop 0
	v_readfirstlane_b32 s10, v0
	s_ashr_i32 s18, s10, 6
	s_mov_b32 s10, s2
	s_lshl_b32 s19, s10, 3
	s_add_i32 s10, s19, s18
	s_cmpk_gt_i32 s10, 0x3fff
	s_cbranch_scc1 .LBB0_1710
	v_cmp_lt_u32_e32 vcc, 0xff, v190
	s_cbranch_vccz .Llnprio_3
	s_setprio 1
.Llnprio_3:
	s_load_dwordx2 s[6:7], s[6:7], 0xe0
	s_ashr_i32 s11, s10, 31
	s_lshl_b64 s[22:23], s[10:11], 12
	s_waitcnt vmcnt(0)
	v_and_b32_e32 v6, 63, v0
	v_lshlrev_b32_e32 v0, 4, v6
	s_waitcnt lgkmcnt(0)
	s_add_u32 s26, s6, s22
	s_addc_u32 s27, s7, s23
	v_lshl_add_u64 v[2:3], s[26:27], 0, v[0:1]
	s_mov_b64 s[26:27], 0x20100000
	v_lshl_add_u64 v[4:5], v[2:3], 0, s[26:27]
	s_mov_b32 s26, 0x20100000
	v_add_co_u32_e32 v2, vcc, s26, v2
	global_load_dwordx4 v[26:29], v[4:5], off offset:1024
	global_load_dwordx4 v[18:21], v[4:5], off offset:2048
	v_addc_co_u32_e32 v3, vcc, 0, v3, vcc
	global_load_dwordx4 v[22:25], v[4:5], off offset:3072
	global_load_dwordx4 v[30:33], v[2:3], off
	s_load_dwordx2 s[26:27], s[8:9], 0xc8
	s_nop 0
	s_load_dwordx2 s[4:5], s[4:5], 0xd0
	s_nop 0
	s_load_dwordx2 s[36:37], s[12:13], 0xe0
	s_nop 0
	s_load_dwordx2 s[14:15], s[14:15], 0xe0
	v_and_b32_e32 v2, 64, v197
	v_xor_b32_e32 v4, 16, v197
	v_add_u32_e32 v10, 64, v2
	v_xor_b32_e32 v8, 32, v197
	v_cmp_lt_i32_e64 s[8:9], v4, v10
	v_lshlrev_b32_e32 v2, 5, v6
	v_mov_b32_e32 v3, v1
	v_cndmask_b32_e64 v11, v197, v4, s[8:9]
	v_cmp_lt_i32_e64 s[8:9], v8, v10
	v_mov_b32_e32 v5, v1
	v_mov_b32_e32 v7, v1
	v_mov_b32_e32 v9, v1
	v_cmp_eq_u32_e32 vcc, 0, v6
	v_cndmask_b32_e64 v10, v197, v8, s[8:9]
	v_or_b32_e32 v4, 0x800, v2
	v_or_b32_e32 v6, 0x1000, v2
	v_or_b32_e32 v8, 0x1800, v2
	s_waitcnt lgkmcnt(0)
	s_cmp_lg_u64 s[14:15], 0
	v_lshl_add_u64 v[36:37], s[4:5], 0, v[2:3]
	v_lshl_add_u64 v[40:41], s[4:5], 0, v[4:5]
	v_lshl_add_u64 v[44:45], s[4:5], 0, v[6:7]
	v_lshl_add_u64 v[48:49], s[4:5], 0, v[8:9]
	s_cselect_b64 s[4:5], -1, 0
	s_lshl_b64 s[8:9], s[10:11], 3
	s_and_b64 s[12:13], s[4:5], vcc
	s_add_u32 s14, s14, s8
	s_addc_u32 s15, s15, s9
	s_add_u32 s64, s36, s22
	s_addc_u32 s65, s37, s23
	s_add_i32 s4, s20, s18
	s_add_i32 s4, s4, s19
	s_ashr_i32 s5, s4, 31
	s_lshl_b64 s[4:5], s[4:5], 12
	v_lshlrev_b32_e32 v68, 2, v11
	v_lshlrev_b32_e32 v69, 2, v10
	v_lshl_add_u64 v[34:35], s[26:27], 0, v[2:3]
	v_lshl_add_u64 v[38:39], s[26:27], 0, v[4:5]
	v_lshl_add_u64 v[42:43], s[26:27], 0, v[6:7]
	v_lshl_add_u64 v[46:47], s[26:27], 0, v[8:9]
	global_load_dwordx4 v[88:91], v[34:35], off
	global_load_dwordx4 v[92:95], v[34:35], off offset:16
	global_load_dwordx4 v[96:99], v[36:37], off
	global_load_dwordx4 v[100:103], v[36:37], off offset:16
	global_load_dwordx4 v[104:107], v[38:39], off
	global_load_dwordx4 v[108:111], v[38:39], off offset:16
	global_load_dwordx4 v[130:133], v[40:41], off
	global_load_dwordx4 v[134:137], v[40:41], off offset:16
	global_load_dwordx4 v[138:141], v[42:43], off
	global_load_dwordx4 v[142:145], v[42:43], off offset:16
	global_load_dwordx4 v[158:161], v[44:45], off
	global_load_dwordx4 v[162:165], v[44:45], off offset:16
	global_load_dwordx4 v[166:169], v[46:47], off
	global_load_dwordx4 v[170:173], v[46:47], off offset:16
	global_load_dwordx4 v[176:179], v[48:49], off
	global_load_dwordx4 v[180:183], v[48:49], off offset:16
	s_add_u32 s68, s6, s4
	s_addc_u32 s69, s7, s5
	s_waitcnt vmcnt(0)
	v_mov_b64_e32 v[6:7], v[26:27]
	s_waitcnt vmcnt(2)
	v_mov_b64_e32 v[2:3], v[18:19]
	v_mov_b64_e32 v[4:5], v[20:21]
	s_waitcnt vmcnt(1)
	v_mov_b64_e32 v[14:15], v[22:23]
	s_waitcnt vmcnt(0)
	v_mov_b64_e32 v[10:11], v[30:31]
	v_mov_b64_e32 v[8:9], v[28:29]
	v_mov_b64_e32 v[16:17], v[24:25]
	v_mov_b64_e32 v[12:13], v[32:33]
	s_branch .LBB0_1706
